# v58 + residual-add epilogues (P3,P6,P8): the 16 h-tile loads per unit marked non-temporal (read once, keeps L2 for the GEMM operand tiles)
# baseline (speedup 1.0000x reference)
; __device__ __forceinline__ unsigned cvt_pk_bf16(float lo, float hi) { unsigned r; asm volatile("v_cvt_pk_bf16_f32 %0, %1, %2" : "=v"(r) : "v"(lo), "v"(hi)); return r; }
;     __device__ __forceinline__ void operator()(const f32x4 (&acc)[2][2][4][2], const Unit& u, int wr, int wc, int fr, int fq) const {
;     ...
;                 for (int bj = 0; bj < 2; ++bj) bw[ai][m][bj] = *(const u32x4*)(hb + (size_t)(row0 + ai * HALF + m * 16) * 1024 + col0 + bj * HALF);
; #pragma unroll
;         for (int ai = 0; ai < 2; ++ai) {
; #pragma unroll
;             for (int m = 0; m < 4; ++m) { const int row = row0 + ai * HALF + m * 16; const size_t off = (size_t)row * 1024 + col0; float ss = 0.f;
; #pragma unroll
;                 for (int bj = 0; bj < 2; ++bj) {
;                     const u32x4 b = bw[ai][m][bj];
;                     const f32x4 b0 = (f32x4){__uint_as_float(b.x << 16), __uint_as_float(b.x & 0xffff0000u), __uint_as_float(b.y << 16), __uint_as_float(b.y & 0xffff0000u)};
;                     const f32x4 b1 = (f32x4){__uint_as_float(b.z << 16), __uint_as_float(b.z & 0xffff0000u), __uint_as_float(b.w << 16), __uint_as_float(b.w & 0xffff0000u)};
;                     const f32x4 v0 = acc[ai][bj][m][0] + b0, v1 = acc[ai][bj][m][1] + b1;
;                     ss += (v0[0] * v0[0] + v0[1] * v0[1]) + (v0[2] * v0[2] + v0[3] * v0[3]) + (v1[0] * v1[0] + v1[1] * v1[1]) + (v1[2] * v1[2] + v1[3] * v1[3]);
;                     u32x4 w; w.x = cvt_pk_bf16(v0[0], v0[1]); w.y = cvt_pk_bf16(v0[2], v0[3]); w.z = cvt_pk_bf16(v1[0], v1[1]); w.w = cvt_pk_bf16(v1[2], v1[3]);
;                     *(u32x4*)(hb + off + bj * HALF) = w; }
;                 ss += __shfl_xor(ss, 16); ss += __shfl_xor(ss, 32);
;                 if (fq == 0) slots[(size_t)row * 16 + u.pn * 4 + wc] = ss; }
.LBB0_593:
	v_lshl_add_u32 v228, s67, 8, v248
	v_lshl_or_b32 v229, s6, 8, v250
	s_lshl_b32 s24, s6, 4
	s_lshl_b32 s86, s61, 2
	v_lshlrev_b32_e32 v240, 6, v228
	v_lshlrev_b32_e32 v228, 11, v228
	s_add_i32 s24, s24, s86
	v_lshl_add_u32 v228, v229, 1, v228
	v_add_u32_e32 v240, s24, v240
	global_load_dwordx4 v[112:115], v228, s[4:5] nt
	global_load_dwordx4 v[120:123], v228, s[4:5] offset:256 nt
	v_add_u32_e32 v229, 0x8000, v228
	global_load_dwordx4 v[124:127], v229, s[4:5] nt
	global_load_dwordx4 v[128:131], v229, s[4:5] offset:256 nt
	v_add_u32_e32 v229, 0x10000, v228
	global_load_dwordx4 v[136:139], v229, s[4:5] nt
	global_load_dwordx4 v[140:143], v229, s[4:5] offset:256 nt
	v_add_u32_e32 v229, 0x18000, v228
	global_load_dwordx4 v[144:147], v229, s[4:5] nt
	global_load_dwordx4 v[156:159], v229, s[4:5] offset:256 nt
	v_add_u32_e32 v229, 0x40000, v228
	global_load_dwordx4 v[160:163], v229, s[4:5] nt
	global_load_dwordx4 v[164:167], v229, s[4:5] offset:256 nt
	v_add_u32_e32 v229, 0x48000, v228
	global_load_dwordx4 v[168:171], v229, s[4:5] nt
	global_load_dwordx4 v[172:175], v229, s[4:5] offset:256 nt
	v_add_u32_e32 v229, 0x50000, v228
	global_load_dwordx4 v[176:179], v229, s[4:5] nt
	global_load_dwordx4 v[180:183], v229, s[4:5] offset:256 nt
	v_add_u32_e32 v229, 0x58000, v228
	global_load_dwordx4 v[184:187], v229, s[4:5] nt
	global_load_dwordx4 v[188:191], v229, s[4:5] offset:256 nt
	v_xor_b32_e32 v230, 16, v252
	v_xor_b32_e32 v231, 32, v252
	v_add_u32_e32 v241, 0x2000, v240
	v_lshlrev_b32_e32 v230, 2, v230
	v_lshlrev_b32_e32 v231, 2, v231
	s_waitcnt vmcnt(14)
	v_lshlrev_b32_e32 v194, 16, v112
	v_and_b32_e32 v195, 0xffff0000, v112
	v_lshlrev_b32_e32 v196, 16, v113
	v_and_b32_e32 v197, 0xffff0000, v113
	v_lshlrev_b32_e32 v208, 16, v114
	v_and_b32_e32 v209, 0xffff0000, v114
	v_lshlrev_b32_e32 v210, 16, v115
	v_and_b32_e32 v211, 0xffff0000, v115
	v_pk_add_f32 v[152:153], v[152:153], v[194:195]
	v_pk_add_f32 v[154:155], v[154:155], v[196:197]
	v_pk_add_f32 v[148:149], v[148:149], v[208:209]
	v_pk_add_f32 v[150:151], v[150:151], v[210:211]
	v_mul_f32_e32 v212, v152, v152
	v_fmac_f32_e32 v212, v153, v153
	v_fmac_f32_e32 v212, v154, v154
	v_fmac_f32_e32 v212, v155, v155
	v_fmac_f32_e32 v212, v148, v148
	v_fmac_f32_e32 v212, v149, v149
	v_fmac_f32_e32 v212, v150, v150
	v_fmac_f32_e32 v212, v151, v151
	v_cvt_pk_bf16_f32 v112, v152, v153
	v_cvt_pk_bf16_f32 v113, v154, v155
	v_cvt_pk_bf16_f32 v114, v148, v149
	v_cvt_pk_bf16_f32 v115, v150, v151
	global_store_dwordx4 v228, v[112:115], s[4:5]
	v_lshlrev_b32_e32 v194, 16, v120
	v_and_b32_e32 v195, 0xffff0000, v120
	v_lshlrev_b32_e32 v196, 16, v121
	v_and_b32_e32 v197, 0xffff0000, v121
	v_lshlrev_b32_e32 v208, 16, v122
	v_and_b32_e32 v209, 0xffff0000, v122
	v_lshlrev_b32_e32 v210, 16, v123
	v_and_b32_e32 v211, 0xffff0000, v123
	v_pk_add_f32 v[132:133], v[132:133], v[194:195]
	v_pk_add_f32 v[134:135], v[134:135], v[196:197]
	v_pk_add_f32 v[116:117], v[116:117], v[208:209]
	v_pk_add_f32 v[118:119], v[118:119], v[210:211]
	v_mul_f32_e32 v220, v132, v132
	v_fmac_f32_e32 v220, v133, v133
	v_fmac_f32_e32 v220, v134, v134
	v_fmac_f32_e32 v220, v135, v135
	v_fmac_f32_e32 v220, v116, v116
	v_fmac_f32_e32 v220, v117, v117
	v_fmac_f32_e32 v220, v118, v118
	v_fmac_f32_e32 v220, v119, v119
	v_cvt_pk_bf16_f32 v120, v132, v133
	v_cvt_pk_bf16_f32 v121, v134, v135
	v_cvt_pk_bf16_f32 v122, v116, v117
	v_cvt_pk_bf16_f32 v123, v118, v119
	global_store_dwordx4 v228, v[120:123], s[4:5] offset:256
	s_waitcnt vmcnt(14)
	v_add_u32_e32 v229, 0x8000, v228
	v_lshlrev_b32_e32 v194, 16, v124
	v_and_b32_e32 v195, 0xffff0000, v124
	v_lshlrev_b32_e32 v196, 16, v125
	v_and_b32_e32 v197, 0xffff0000, v125
	v_lshlrev_b32_e32 v208, 16, v126
	v_and_b32_e32 v209, 0xffff0000, v126
	v_lshlrev_b32_e32 v210, 16, v127
	v_and_b32_e32 v211, 0xffff0000, v127
	v_pk_add_f32 v[108:109], v[108:109], v[194:195]
	v_pk_add_f32 v[110:111], v[110:111], v[196:197]
	v_pk_add_f32 v[104:105], v[104:105], v[208:209]
	v_pk_add_f32 v[106:107], v[106:107], v[210:211]
	v_mul_f32_e32 v213, v108, v108
	v_fmac_f32_e32 v213, v109, v109
	v_fmac_f32_e32 v213, v110, v110
	v_fmac_f32_e32 v213, v111, v111
	v_fmac_f32_e32 v213, v104, v104
	v_fmac_f32_e32 v213, v105, v105
	v_fmac_f32_e32 v213, v106, v106
	v_fmac_f32_e32 v213, v107, v107
	v_cvt_pk_bf16_f32 v124, v108, v109
	v_cvt_pk_bf16_f32 v125, v110, v111
	v_cvt_pk_bf16_f32 v126, v104, v105
	v_cvt_pk_bf16_f32 v127, v106, v107
	global_store_dwordx4 v229, v[124:127], s[4:5]
	v_lshlrev_b32_e32 v194, 16, v128
	v_and_b32_e32 v195, 0xffff0000, v128
	v_lshlrev_b32_e32 v196, 16, v129
	v_and_b32_e32 v197, 0xffff0000, v129
	v_lshlrev_b32_e32 v208, 16, v130
	v_and_b32_e32 v209, 0xffff0000, v130
	v_lshlrev_b32_e32 v210, 16, v131
	v_and_b32_e32 v211, 0xffff0000, v131
	v_pk_add_f32 v[100:101], v[100:101], v[194:195]
	v_pk_add_f32 v[102:103], v[102:103], v[196:197]
	v_pk_add_f32 v[96:97], v[96:97], v[208:209]
	v_pk_add_f32 v[98:99], v[98:99], v[210:211]
	v_mul_f32_e32 v221, v100, v100
	v_fmac_f32_e32 v221, v101, v101
	v_fmac_f32_e32 v221, v102, v102
	v_fmac_f32_e32 v221, v103, v103
	v_fmac_f32_e32 v221, v96, v96
	v_fmac_f32_e32 v221, v97, v97
	v_fmac_f32_e32 v221, v98, v98
	v_fmac_f32_e32 v221, v99, v99
	v_cvt_pk_bf16_f32 v128, v100, v101
	v_cvt_pk_bf16_f32 v129, v102, v103
	v_cvt_pk_bf16_f32 v130, v96, v97
	v_cvt_pk_bf16_f32 v131, v98, v99
	global_store_dwordx4 v229, v[128:131], s[4:5] offset:256
	s_waitcnt vmcnt(14)
; __device__ __forceinline__ unsigned cvt_pk_bf16(float lo, float hi) { unsigned r; asm volatile("v_cvt_pk_bf16_f32 %0, %1, %2" : "=v"(r) : "v"(lo), "v"(hi)); return r; }
;     __device__ __forceinline__ void operator()(const f32x4 (&acc)[2][2][4][2], const Unit& u, int wr, int wc, int fr, int fq) const {
;     ...
;             for (int m = 0; m < 4; ++m) { const int row = row0 + ai * HALF + m * 16; const size_t off = (size_t)row * 1024 + col0; float ss = 0.f;
; #pragma unroll
;                 for (int bj = 0; bj < 2; ++bj) {
;                     const u32x4 b = bw[ai][m][bj];
;                     const f32x4 b0 = (f32x4){__uint_as_float(b.x << 16), __uint_as_float(b.x & 0xffff0000u), __uint_as_float(b.y << 16), __uint_as_float(b.y & 0xffff0000u)};
;                     const f32x4 b1 = (f32x4){__uint_as_float(b.z << 16), __uint_as_float(b.z & 0xffff0000u), __uint_as_float(b.w << 16), __uint_as_float(b.w & 0xffff0000u)};
;                     const f32x4 v0 = acc[ai][bj][m][0] + b0, v1 = acc[ai][bj][m][1] + b1;
;                     ss += (v0[0] * v0[0] + v0[1] * v0[1]) + (v0[2] * v0[2] + v0[3] * v0[3]) + (v1[0] * v1[0] + v1[1] * v1[1]) + (v1[2] * v1[2] + v1[3] * v1[3]);
;                     u32x4 w; w.x = cvt_pk_bf16(v0[0], v0[1]); w.y = cvt_pk_bf16(v0[2], v0[3]); w.z = cvt_pk_bf16(v1[0], v1[1]); w.w = cvt_pk_bf16(v1[2], v1[3]);
;                     *(u32x4*)(hb + off + bj * HALF) = w; }
	v_add_u32_e32 v229, 0x10000, v228
	v_lshlrev_b32_e32 v194, 16, v136
	v_and_b32_e32 v195, 0xffff0000, v136
	v_lshlrev_b32_e32 v196, 16, v137
	v_and_b32_e32 v197, 0xffff0000, v137
	v_lshlrev_b32_e32 v208, 16, v138
	v_and_b32_e32 v209, 0xffff0000, v138
	v_lshlrev_b32_e32 v210, 16, v139
	v_and_b32_e32 v211, 0xffff0000, v139
	v_pk_add_f32 v[92:93], v[92:93], v[194:195]
	v_pk_add_f32 v[94:95], v[94:95], v[196:197]
	v_pk_add_f32 v[88:89], v[88:89], v[208:209]
	v_pk_add_f32 v[90:91], v[90:91], v[210:211]
	v_mul_f32_e32 v214, v92, v92
	v_fmac_f32_e32 v214, v93, v93
	v_fmac_f32_e32 v214, v94, v94
	v_fmac_f32_e32 v214, v95, v95
	v_fmac_f32_e32 v214, v88, v88
	v_fmac_f32_e32 v214, v89, v89
	v_fmac_f32_e32 v214, v90, v90
	v_fmac_f32_e32 v214, v91, v91
	v_cvt_pk_bf16_f32 v136, v92, v93
	v_cvt_pk_bf16_f32 v137, v94, v95
	v_cvt_pk_bf16_f32 v138, v88, v89
	v_cvt_pk_bf16_f32 v139, v90, v91
	global_store_dwordx4 v229, v[136:139], s[4:5]
	v_lshlrev_b32_e32 v194, 16, v140
	v_and_b32_e32 v195, 0xffff0000, v140
	v_lshlrev_b32_e32 v196, 16, v141
	v_and_b32_e32 v197, 0xffff0000, v141
	v_lshlrev_b32_e32 v208, 16, v142
	v_and_b32_e32 v209, 0xffff0000, v142
	v_lshlrev_b32_e32 v210, 16, v143
	v_and_b32_e32 v211, 0xffff0000, v143
	v_pk_add_f32 v[84:85], v[84:85], v[194:195]
	v_pk_add_f32 v[86:87], v[86:87], v[196:197]
	v_pk_add_f32 v[80:81], v[80:81], v[208:209]
	v_pk_add_f32 v[82:83], v[82:83], v[210:211]
	v_mul_f32_e32 v222, v84, v84
	v_fmac_f32_e32 v222, v85, v85
	v_fmac_f32_e32 v222, v86, v86
	v_fmac_f32_e32 v222, v87, v87
	v_fmac_f32_e32 v222, v80, v80
	v_fmac_f32_e32 v222, v81, v81
	v_fmac_f32_e32 v222, v82, v82
	v_fmac_f32_e32 v222, v83, v83
	v_cvt_pk_bf16_f32 v140, v84, v85
	v_cvt_pk_bf16_f32 v141, v86, v87
	v_cvt_pk_bf16_f32 v142, v80, v81
	v_cvt_pk_bf16_f32 v143, v82, v83
	global_store_dwordx4 v229, v[140:143], s[4:5] offset:256
	s_waitcnt vmcnt(14)
	v_add_u32_e32 v229, 0x18000, v228
	v_lshlrev_b32_e32 v194, 16, v144
	v_and_b32_e32 v195, 0xffff0000, v144
	v_lshlrev_b32_e32 v196, 16, v145
	v_and_b32_e32 v197, 0xffff0000, v145
	v_lshlrev_b32_e32 v208, 16, v146
	v_and_b32_e32 v209, 0xffff0000, v146
	v_lshlrev_b32_e32 v210, 16, v147
	v_and_b32_e32 v211, 0xffff0000, v147
	v_pk_add_f32 v[76:77], v[76:77], v[194:195]
	v_pk_add_f32 v[78:79], v[78:79], v[196:197]
	v_pk_add_f32 v[72:73], v[72:73], v[208:209]
	v_pk_add_f32 v[74:75], v[74:75], v[210:211]
	v_mul_f32_e32 v215, v76, v76
	v_fmac_f32_e32 v215, v77, v77
	v_fmac_f32_e32 v215, v78, v78
	v_fmac_f32_e32 v215, v79, v79
	v_fmac_f32_e32 v215, v72, v72
	v_fmac_f32_e32 v215, v73, v73
	v_fmac_f32_e32 v215, v74, v74
	v_fmac_f32_e32 v215, v75, v75
	v_cvt_pk_bf16_f32 v144, v76, v77
	v_cvt_pk_bf16_f32 v145, v78, v79
	v_cvt_pk_bf16_f32 v146, v72, v73
	v_cvt_pk_bf16_f32 v147, v74, v75
	global_store_dwordx4 v229, v[144:147], s[4:5]
	v_lshlrev_b32_e32 v194, 16, v156
	v_and_b32_e32 v195, 0xffff0000, v156
	v_lshlrev_b32_e32 v196, 16, v157
	v_and_b32_e32 v197, 0xffff0000, v157
	v_lshlrev_b32_e32 v208, 16, v158
	v_and_b32_e32 v209, 0xffff0000, v158
	v_lshlrev_b32_e32 v210, 16, v159
	v_and_b32_e32 v211, 0xffff0000, v159
	v_pk_add_f32 v[68:69], v[68:69], v[194:195]
	v_pk_add_f32 v[70:71], v[70:71], v[196:197]
	v_pk_add_f32 v[64:65], v[64:65], v[208:209]
	v_pk_add_f32 v[66:67], v[66:67], v[210:211]
	v_mul_f32_e32 v223, v68, v68
	v_fmac_f32_e32 v223, v69, v69
	v_fmac_f32_e32 v223, v70, v70
	v_fmac_f32_e32 v223, v71, v71
	v_fmac_f32_e32 v223, v64, v64
	v_fmac_f32_e32 v223, v65, v65
	v_fmac_f32_e32 v223, v66, v66
	v_fmac_f32_e32 v223, v67, v67
	v_cvt_pk_bf16_f32 v156, v68, v69
	v_cvt_pk_bf16_f32 v157, v70, v71
	v_cvt_pk_bf16_f32 v158, v64, v65
	v_cvt_pk_bf16_f32 v159, v66, v67
	global_store_dwordx4 v229, v[156:159], s[4:5] offset:256
	s_waitcnt vmcnt(14)
	v_add_u32_e32 v229, 0x40000, v228
	v_lshlrev_b32_e32 v194, 16, v160
	v_and_b32_e32 v195, 0xffff0000, v160
	v_lshlrev_b32_e32 v196, 16, v161
	v_and_b32_e32 v197, 0xffff0000, v161
	v_lshlrev_b32_e32 v208, 16, v162
	v_and_b32_e32 v209, 0xffff0000, v162
	v_lshlrev_b32_e32 v210, 16, v163
	v_and_b32_e32 v211, 0xffff0000, v163
	v_pk_add_f32 v[60:61], v[60:61], v[194:195]
	v_pk_add_f32 v[62:63], v[62:63], v[196:197]
	v_pk_add_f32 v[56:57], v[56:57], v[208:209]
	v_pk_add_f32 v[58:59], v[58:59], v[210:211]
	v_mul_f32_e32 v216, v60, v60
	v_fmac_f32_e32 v216, v61, v61
	v_fmac_f32_e32 v216, v62, v62
	v_fmac_f32_e32 v216, v63, v63
	v_fmac_f32_e32 v216, v56, v56
	v_fmac_f32_e32 v216, v57, v57
	v_fmac_f32_e32 v216, v58, v58
	v_fmac_f32_e32 v216, v59, v59
	v_cvt_pk_bf16_f32 v160, v60, v61
	v_cvt_pk_bf16_f32 v161, v62, v63
	v_cvt_pk_bf16_f32 v162, v56, v57
	v_cvt_pk_bf16_f32 v163, v58, v59
	global_store_dwordx4 v229, v[160:163], s[4:5]
	v_lshlrev_b32_e32 v194, 16, v164
	v_and_b32_e32 v195, 0xffff0000, v164
	v_lshlrev_b32_e32 v196, 16, v165
	v_and_b32_e32 v197, 0xffff0000, v165
	v_lshlrev_b32_e32 v208, 16, v166
	v_and_b32_e32 v209, 0xffff0000, v166
	v_lshlrev_b32_e32 v210, 16, v167
	v_and_b32_e32 v211, 0xffff0000, v167
	v_pk_add_f32 v[52:53], v[52:53], v[194:195]
	v_pk_add_f32 v[54:55], v[54:55], v[196:197]
	v_pk_add_f32 v[48:49], v[48:49], v[208:209]
	v_pk_add_f32 v[50:51], v[50:51], v[210:211]
	v_mul_f32_e32 v224, v52, v52
	v_fmac_f32_e32 v224, v53, v53
	v_fmac_f32_e32 v224, v54, v54
	v_fmac_f32_e32 v224, v55, v55
	v_fmac_f32_e32 v224, v48, v48
	v_fmac_f32_e32 v224, v49, v49
	v_fmac_f32_e32 v224, v50, v50
	v_fmac_f32_e32 v224, v51, v51
	v_cvt_pk_bf16_f32 v164, v52, v53
	v_cvt_pk_bf16_f32 v165, v54, v55
	v_cvt_pk_bf16_f32 v166, v48, v49
	v_cvt_pk_bf16_f32 v167, v50, v51
	global_store_dwordx4 v229, v[164:167], s[4:5] offset:256
	s_waitcnt vmcnt(14)
; __device__ __forceinline__ unsigned cvt_pk_bf16(float lo, float hi) { unsigned r; asm volatile("v_cvt_pk_bf16_f32 %0, %1, %2" : "=v"(r) : "v"(lo), "v"(hi)); return r; }
;     __device__ __forceinline__ void operator()(const f32x4 (&acc)[2][2][4][2], const Unit& u, int wr, int wc, int fr, int fq) const {
;     ...
;             for (int m = 0; m < 4; ++m) { const int row = row0 + ai * HALF + m * 16; const size_t off = (size_t)row * 1024 + col0; float ss = 0.f;
; #pragma unroll
;                 for (int bj = 0; bj < 2; ++bj) {
;                     const u32x4 b = bw[ai][m][bj];
;                     const f32x4 b0 = (f32x4){__uint_as_float(b.x << 16), __uint_as_float(b.x & 0xffff0000u), __uint_as_float(b.y << 16), __uint_as_float(b.y & 0xffff0000u)};
;                     const f32x4 b1 = (f32x4){__uint_as_float(b.z << 16), __uint_as_float(b.z & 0xffff0000u), __uint_as_float(b.w << 16), __uint_as_float(b.w & 0xffff0000u)};
;                     const f32x4 v0 = acc[ai][bj][m][0] + b0, v1 = acc[ai][bj][m][1] + b1;
;                     ss += (v0[0] * v0[0] + v0[1] * v0[1]) + (v0[2] * v0[2] + v0[3] * v0[3]) + (v1[0] * v1[0] + v1[1] * v1[1]) + (v1[2] * v1[2] + v1[3] * v1[3]);
;                     u32x4 w; w.x = cvt_pk_bf16(v0[0], v0[1]); w.y = cvt_pk_bf16(v0[2], v0[3]); w.z = cvt_pk_bf16(v1[0], v1[1]); w.w = cvt_pk_bf16(v1[2], v1[3]);
;                     *(u32x4*)(hb + off + bj * HALF) = w; }
	v_add_u32_e32 v229, 0x48000, v228
	v_lshlrev_b32_e32 v194, 16, v168
	v_and_b32_e32 v195, 0xffff0000, v168
	v_lshlrev_b32_e32 v196, 16, v169
	v_and_b32_e32 v197, 0xffff0000, v169
	v_lshlrev_b32_e32 v208, 16, v170
	v_and_b32_e32 v209, 0xffff0000, v170
	v_lshlrev_b32_e32 v210, 16, v171
	v_and_b32_e32 v211, 0xffff0000, v171
	v_pk_add_f32 v[44:45], v[44:45], v[194:195]
	v_pk_add_f32 v[46:47], v[46:47], v[196:197]
	v_pk_add_f32 v[40:41], v[40:41], v[208:209]
	v_pk_add_f32 v[42:43], v[42:43], v[210:211]
	v_mul_f32_e32 v217, v44, v44
	v_fmac_f32_e32 v217, v45, v45
	v_fmac_f32_e32 v217, v46, v46
	v_fmac_f32_e32 v217, v47, v47
	v_fmac_f32_e32 v217, v40, v40
	v_fmac_f32_e32 v217, v41, v41
	v_fmac_f32_e32 v217, v42, v42
	v_fmac_f32_e32 v217, v43, v43
	v_cvt_pk_bf16_f32 v168, v44, v45
	v_cvt_pk_bf16_f32 v169, v46, v47
	v_cvt_pk_bf16_f32 v170, v40, v41
	v_cvt_pk_bf16_f32 v171, v42, v43
	global_store_dwordx4 v229, v[168:171], s[4:5]
	v_lshlrev_b32_e32 v194, 16, v172
	v_and_b32_e32 v195, 0xffff0000, v172
	v_lshlrev_b32_e32 v196, 16, v173
	v_and_b32_e32 v197, 0xffff0000, v173
	v_lshlrev_b32_e32 v208, 16, v174
	v_and_b32_e32 v209, 0xffff0000, v174
	v_lshlrev_b32_e32 v210, 16, v175
	v_and_b32_e32 v211, 0xffff0000, v175
	v_pk_add_f32 v[36:37], v[36:37], v[194:195]
	v_pk_add_f32 v[38:39], v[38:39], v[196:197]
	v_pk_add_f32 v[32:33], v[32:33], v[208:209]
	v_pk_add_f32 v[34:35], v[34:35], v[210:211]
	v_mul_f32_e32 v225, v36, v36
	v_fmac_f32_e32 v225, v37, v37
	v_fmac_f32_e32 v225, v38, v38
	v_fmac_f32_e32 v225, v39, v39
	v_fmac_f32_e32 v225, v32, v32
	v_fmac_f32_e32 v225, v33, v33
	v_fmac_f32_e32 v225, v34, v34
	v_fmac_f32_e32 v225, v35, v35
	v_cvt_pk_bf16_f32 v172, v36, v37
	v_cvt_pk_bf16_f32 v173, v38, v39
	v_cvt_pk_bf16_f32 v174, v32, v33
	v_cvt_pk_bf16_f32 v175, v34, v35
	global_store_dwordx4 v229, v[172:175], s[4:5] offset:256
	s_waitcnt vmcnt(14)
	v_add_u32_e32 v229, 0x50000, v228
	v_lshlrev_b32_e32 v194, 16, v176
	v_and_b32_e32 v195, 0xffff0000, v176
	v_lshlrev_b32_e32 v196, 16, v177
	v_and_b32_e32 v197, 0xffff0000, v177
	v_lshlrev_b32_e32 v208, 16, v178
	v_and_b32_e32 v209, 0xffff0000, v178
	v_lshlrev_b32_e32 v210, 16, v179
	v_and_b32_e32 v211, 0xffff0000, v179
	v_pk_add_f32 v[28:29], v[28:29], v[194:195]
	v_pk_add_f32 v[30:31], v[30:31], v[196:197]
	v_pk_add_f32 v[24:25], v[24:25], v[208:209]
	v_pk_add_f32 v[26:27], v[26:27], v[210:211]
	v_mul_f32_e32 v218, v28, v28
	v_fmac_f32_e32 v218, v29, v29
	v_fmac_f32_e32 v218, v30, v30
	v_fmac_f32_e32 v218, v31, v31
	v_fmac_f32_e32 v218, v24, v24
	v_fmac_f32_e32 v218, v25, v25
	v_fmac_f32_e32 v218, v26, v26
	v_fmac_f32_e32 v218, v27, v27
	v_cvt_pk_bf16_f32 v176, v28, v29
	v_cvt_pk_bf16_f32 v177, v30, v31
	v_cvt_pk_bf16_f32 v178, v24, v25
	v_cvt_pk_bf16_f32 v179, v26, v27
	global_store_dwordx4 v229, v[176:179], s[4:5]
	v_lshlrev_b32_e32 v194, 16, v180
	v_and_b32_e32 v195, 0xffff0000, v180
	v_lshlrev_b32_e32 v196, 16, v181
	v_and_b32_e32 v197, 0xffff0000, v181
	v_lshlrev_b32_e32 v208, 16, v182
	v_and_b32_e32 v209, 0xffff0000, v182
	v_lshlrev_b32_e32 v210, 16, v183
	v_and_b32_e32 v211, 0xffff0000, v183
	v_pk_add_f32 v[20:21], v[20:21], v[194:195]
	v_pk_add_f32 v[22:23], v[22:23], v[196:197]
	v_pk_add_f32 v[16:17], v[16:17], v[208:209]
	v_pk_add_f32 v[18:19], v[18:19], v[210:211]
	v_mul_f32_e32 v226, v20, v20
	v_fmac_f32_e32 v226, v21, v21
	v_fmac_f32_e32 v226, v22, v22
	v_fmac_f32_e32 v226, v23, v23
	v_fmac_f32_e32 v226, v16, v16
	v_fmac_f32_e32 v226, v17, v17
	v_fmac_f32_e32 v226, v18, v18
	v_fmac_f32_e32 v226, v19, v19
	v_cvt_pk_bf16_f32 v180, v20, v21
	v_cvt_pk_bf16_f32 v181, v22, v23
	v_cvt_pk_bf16_f32 v182, v16, v17
	v_cvt_pk_bf16_f32 v183, v18, v19
	global_store_dwordx4 v229, v[180:183], s[4:5] offset:256
	s_waitcnt vmcnt(14)
; __device__ __forceinline__ unsigned cvt_pk_bf16(float lo, float hi) { unsigned r; asm volatile("v_cvt_pk_bf16_f32 %0, %1, %2" : "=v"(r) : "v"(lo), "v"(hi)); return r; }
;     __device__ __forceinline__ void operator()(const f32x4 (&acc)[2][2][4][2], const Unit& u, int wr, int wc, int fr, int fq) const {
;     ...
;             for (int m = 0; m < 4; ++m) { const int row = row0 + ai * HALF + m * 16; const size_t off = (size_t)row * 1024 + col0; float ss = 0.f;
; #pragma unroll
;                 for (int bj = 0; bj < 2; ++bj) {
;                     const u32x4 b = bw[ai][m][bj];
;                     const f32x4 b0 = (f32x4){__uint_as_float(b.x << 16), __uint_as_float(b.x & 0xffff0000u), __uint_as_float(b.y << 16), __uint_as_float(b.y & 0xffff0000u)};
;                     const f32x4 b1 = (f32x4){__uint_as_float(b.z << 16), __uint_as_float(b.z & 0xffff0000u), __uint_as_float(b.w << 16), __uint_as_float(b.w & 0xffff0000u)};
;                     const f32x4 v0 = acc[ai][bj][m][0] + b0, v1 = acc[ai][bj][m][1] + b1;
;                     ss += (v0[0] * v0[0] + v0[1] * v0[1]) + (v0[2] * v0[2] + v0[3] * v0[3]) + (v1[0] * v1[0] + v1[1] * v1[1]) + (v1[2] * v1[2] + v1[3] * v1[3]);
;                     u32x4 w; w.x = cvt_pk_bf16(v0[0], v0[1]); w.y = cvt_pk_bf16(v0[2], v0[3]); w.z = cvt_pk_bf16(v1[0], v1[1]); w.w = cvt_pk_bf16(v1[2], v1[3]);
;                     *(u32x4*)(hb + off + bj * HALF) = w; }
;                 ss += __shfl_xor(ss, 16); ss += __shfl_xor(ss, 32);
;                 if (fq == 0) slots[(size_t)row * 16 + u.pn * 4 + wc] = ss; }
	v_add_u32_e32 v229, 0x58000, v228
	v_lshlrev_b32_e32 v194, 16, v184
	v_and_b32_e32 v195, 0xffff0000, v184
	v_lshlrev_b32_e32 v196, 16, v185
	v_and_b32_e32 v197, 0xffff0000, v185
	v_lshlrev_b32_e32 v208, 16, v186
	v_and_b32_e32 v209, 0xffff0000, v186
	v_lshlrev_b32_e32 v210, 16, v187
	v_and_b32_e32 v211, 0xffff0000, v187
	v_pk_add_f32 v[12:13], v[12:13], v[194:195]
	v_pk_add_f32 v[14:15], v[14:15], v[196:197]
	v_pk_add_f32 v[8:9], v[8:9], v[208:209]
	v_pk_add_f32 v[10:11], v[10:11], v[210:211]
	v_mul_f32_e32 v219, v12, v12
	v_fmac_f32_e32 v219, v13, v13
	v_fmac_f32_e32 v219, v14, v14
	v_fmac_f32_e32 v219, v15, v15
	v_fmac_f32_e32 v219, v8, v8
	v_fmac_f32_e32 v219, v9, v9
	v_fmac_f32_e32 v219, v10, v10
	v_fmac_f32_e32 v219, v11, v11
	v_cvt_pk_bf16_f32 v184, v12, v13
	v_cvt_pk_bf16_f32 v185, v14, v15
	v_cvt_pk_bf16_f32 v186, v8, v9
	v_cvt_pk_bf16_f32 v187, v10, v11
	global_store_dwordx4 v229, v[184:187], s[4:5]
	v_lshlrev_b32_e32 v194, 16, v188
	v_and_b32_e32 v195, 0xffff0000, v188
	v_lshlrev_b32_e32 v196, 16, v189
	v_and_b32_e32 v197, 0xffff0000, v189
	v_lshlrev_b32_e32 v208, 16, v190
	v_and_b32_e32 v209, 0xffff0000, v190
	v_lshlrev_b32_e32 v210, 16, v191
	v_and_b32_e32 v211, 0xffff0000, v191
	v_pk_add_f32 v[4:5], v[4:5], v[194:195]
	v_pk_add_f32 v[6:7], v[6:7], v[196:197]
	v_pk_add_f32 v[0:1], v[0:1], v[208:209]
	v_pk_add_f32 v[2:3], v[2:3], v[210:211]
	v_mul_f32_e32 v227, v4, v4
	v_fmac_f32_e32 v227, v5, v5
	v_fmac_f32_e32 v227, v6, v6
	v_fmac_f32_e32 v227, v7, v7
	v_fmac_f32_e32 v227, v0, v0
	v_fmac_f32_e32 v227, v1, v1
	v_fmac_f32_e32 v227, v2, v2
	v_fmac_f32_e32 v227, v3, v3
	v_cvt_pk_bf16_f32 v188, v4, v5
	v_cvt_pk_bf16_f32 v189, v6, v7
	v_cvt_pk_bf16_f32 v190, v0, v1
	v_cvt_pk_bf16_f32 v191, v2, v3
	global_store_dwordx4 v229, v[188:191], s[4:5] offset:256
	v_add_f32_e32 v212, v212, v220
	v_add_f32_e32 v213, v213, v221
	v_add_f32_e32 v214, v214, v222
	v_add_f32_e32 v215, v215, v223
	v_add_f32_e32 v216, v216, v224
	v_add_f32_e32 v217, v217, v225
	v_add_f32_e32 v218, v218, v226
	v_add_f32_e32 v219, v219, v227
	ds_bpermute_b32 v232, v230, v212
	ds_bpermute_b32 v233, v230, v213
	ds_bpermute_b32 v234, v230, v214
	ds_bpermute_b32 v235, v230, v215
	ds_bpermute_b32 v236, v230, v216
	ds_bpermute_b32 v237, v230, v217
	ds_bpermute_b32 v238, v230, v218
	ds_bpermute_b32 v239, v230, v219
	s_waitcnt lgkmcnt(0)
	v_add_f32_e32 v212, v212, v232
	v_add_f32_e32 v213, v213, v233
	v_add_f32_e32 v214, v214, v234
	v_add_f32_e32 v215, v215, v235
	v_add_f32_e32 v216, v216, v236
	v_add_f32_e32 v217, v217, v237
	v_add_f32_e32 v218, v218, v238
	v_add_f32_e32 v219, v219, v239
	ds_bpermute_b32 v232, v231, v212
	ds_bpermute_b32 v233, v231, v213
	ds_bpermute_b32 v234, v231, v214
	ds_bpermute_b32 v235, v231, v215
	ds_bpermute_b32 v236, v231, v216
	ds_bpermute_b32 v237, v231, v217
	ds_bpermute_b32 v238, v231, v218
	ds_bpermute_b32 v239, v231, v219
	s_waitcnt lgkmcnt(0)
	v_add_f32_e32 v212, v212, v232
	v_add_f32_e32 v213, v213, v233
	v_add_f32_e32 v214, v214, v234
	v_add_f32_e32 v215, v215, v235
	v_add_f32_e32 v216, v216, v236
	v_add_f32_e32 v217, v217, v237
	v_add_f32_e32 v218, v218, v238
	v_add_f32_e32 v219, v219, v239
	s_and_saveexec_b64 s[24:25], s[40:41]
	global_store_dword v240, v212, s[10:11]
	global_store_dword v240, v213, s[10:11] offset:1024
	global_store_dword v240, v214, s[10:11] offset:2048
	global_store_dword v240, v215, s[10:11] offset:3072
	global_store_dword v241, v216, s[10:11]
	global_store_dword v241, v217, s[10:11] offset:1024
	global_store_dword v241, v218, s[10:11] offset:2048
	global_store_dword v241, v219, s[10:11] offset:3072
	s_or_b64 exec, exec, s[24:25]
	s_and_b64 vcc, exec, s[42:43]
	s_mov_b64 s[22:23], -1
	s_cbranch_vccnz .LBB0_580
	s_andn2_b64 vcc, exec, s[0:1]
	s_cbranch_vccnz .LBB0_579
	s_barrier
	s_branch .LBB0_579

; __device__ __forceinline__ unsigned cvt_pk_bf16(float lo, float hi) { unsigned r; asm volatile("v_cvt_pk_bf16_f32 %0, %1, %2" : "=v"(r) : "v"(lo), "v"(hi)); return r; }
;     __device__ __forceinline__ void operator()(const f32x4 (&acc)[2][2][4][2], const Unit& u, int wr, int wc, int fr, int fq) const {
;     ...
;                 for (int bj = 0; bj < 2; ++bj) bw[ai][m][bj] = *(const u32x4*)(hb + (size_t)(row0 + ai * HALF + m * 16) * 1024 + col0 + bj * HALF);
; #pragma unroll
;         for (int ai = 0; ai < 2; ++ai) {
; #pragma unroll
;             for (int m = 0; m < 4; ++m) { const int row = row0 + ai * HALF + m * 16; const size_t off = (size_t)row * 1024 + col0; float ss = 0.f;
; #pragma unroll
;                 for (int bj = 0; bj < 2; ++bj) {
;                     const u32x4 b = bw[ai][m][bj];
;                     const f32x4 b0 = (f32x4){__uint_as_float(b.x << 16), __uint_as_float(b.x & 0xffff0000u), __uint_as_float(b.y << 16), __uint_as_float(b.y & 0xffff0000u)};
;                     const f32x4 b1 = (f32x4){__uint_as_float(b.z << 16), __uint_as_float(b.z & 0xffff0000u), __uint_as_float(b.w << 16), __uint_as_float(b.w & 0xffff0000u)};
;                     const f32x4 v0 = acc[ai][bj][m][0] + b0, v1 = acc[ai][bj][m][1] + b1;
;                     ss += (v0[0] * v0[0] + v0[1] * v0[1]) + (v0[2] * v0[2] + v0[3] * v0[3]) + (v1[0] * v1[0] + v1[1] * v1[1]) + (v1[2] * v1[2] + v1[3] * v1[3]);
;                     u32x4 w; w.x = cvt_pk_bf16(v0[0], v0[1]); w.y = cvt_pk_bf16(v0[2], v0[3]); w.z = cvt_pk_bf16(v1[0], v1[1]); w.w = cvt_pk_bf16(v1[2], v1[3]);
;                     *(u32x4*)(hb + off + bj * HALF) = w; }
;                 ss += __shfl_xor(ss, 16); ss += __shfl_xor(ss, 32);
;                 if (fq == 0) slots[(size_t)row * 16 + u.pn * 4 + wc] = ss; }
.LBB0_1034:
	v_lshl_add_u32 v228, s71, 8, v248
	v_lshl_or_b32 v229, s6, 8, v250
	s_lshl_b32 s20, s6, 4
	s_lshl_b32 s86, s61, 2
	v_lshlrev_b32_e32 v240, 6, v228
	v_lshlrev_b32_e32 v228, 11, v228
	s_add_i32 s20, s20, s86
	v_lshl_add_u32 v228, v229, 1, v228
	v_add_u32_e32 v240, s20, v240
	global_load_dwordx4 v[112:115], v228, s[4:5] nt
	global_load_dwordx4 v[120:123], v228, s[4:5] offset:256 nt
	v_add_u32_e32 v229, 0x8000, v228
	global_load_dwordx4 v[124:127], v229, s[4:5] nt
	global_load_dwordx4 v[128:131], v229, s[4:5] offset:256 nt
	v_add_u32_e32 v229, 0x10000, v228
	global_load_dwordx4 v[136:139], v229, s[4:5] nt
	global_load_dwordx4 v[140:143], v229, s[4:5] offset:256 nt
	v_add_u32_e32 v229, 0x18000, v228
	global_load_dwordx4 v[144:147], v229, s[4:5] nt
	global_load_dwordx4 v[156:159], v229, s[4:5] offset:256 nt
	v_add_u32_e32 v229, 0x40000, v228
	global_load_dwordx4 v[160:163], v229, s[4:5] nt
	global_load_dwordx4 v[164:167], v229, s[4:5] offset:256 nt
	v_add_u32_e32 v229, 0x48000, v228
	global_load_dwordx4 v[168:171], v229, s[4:5] nt
	global_load_dwordx4 v[172:175], v229, s[4:5] offset:256 nt
	v_add_u32_e32 v229, 0x50000, v228
	global_load_dwordx4 v[176:179], v229, s[4:5] nt
	global_load_dwordx4 v[180:183], v229, s[4:5] offset:256 nt
	v_add_u32_e32 v229, 0x58000, v228
	global_load_dwordx4 v[184:187], v229, s[4:5] nt
	global_load_dwordx4 v[188:191], v229, s[4:5] offset:256 nt
	v_xor_b32_e32 v230, 16, v252
	v_xor_b32_e32 v231, 32, v252
	v_add_u32_e32 v241, 0x2000, v240
	v_lshlrev_b32_e32 v230, 2, v230
	v_lshlrev_b32_e32 v231, 2, v231
	s_waitcnt vmcnt(14)
	v_lshlrev_b32_e32 v194, 16, v112
	v_and_b32_e32 v195, 0xffff0000, v112
	v_lshlrev_b32_e32 v196, 16, v113
	v_and_b32_e32 v197, 0xffff0000, v113
	v_lshlrev_b32_e32 v208, 16, v114
	v_and_b32_e32 v209, 0xffff0000, v114
	v_lshlrev_b32_e32 v210, 16, v115
	v_and_b32_e32 v211, 0xffff0000, v115
	v_pk_add_f32 v[152:153], v[152:153], v[194:195]
	v_pk_add_f32 v[154:155], v[154:155], v[196:197]
	v_pk_add_f32 v[148:149], v[148:149], v[208:209]
	v_pk_add_f32 v[150:151], v[150:151], v[210:211]
	v_mul_f32_e32 v212, v152, v152
	v_fmac_f32_e32 v212, v153, v153
	v_fmac_f32_e32 v212, v154, v154
	v_fmac_f32_e32 v212, v155, v155
	v_fmac_f32_e32 v212, v148, v148
	v_fmac_f32_e32 v212, v149, v149
	v_fmac_f32_e32 v212, v150, v150
	v_fmac_f32_e32 v212, v151, v151
	v_cvt_pk_bf16_f32 v112, v152, v153
	v_cvt_pk_bf16_f32 v113, v154, v155
	v_cvt_pk_bf16_f32 v114, v148, v149
	v_cvt_pk_bf16_f32 v115, v150, v151
	global_store_dwordx4 v228, v[112:115], s[4:5]
	v_lshlrev_b32_e32 v194, 16, v120
	v_and_b32_e32 v195, 0xffff0000, v120
	v_lshlrev_b32_e32 v196, 16, v121
	v_and_b32_e32 v197, 0xffff0000, v121
	v_lshlrev_b32_e32 v208, 16, v122
	v_and_b32_e32 v209, 0xffff0000, v122
	v_lshlrev_b32_e32 v210, 16, v123
	v_and_b32_e32 v211, 0xffff0000, v123
	v_pk_add_f32 v[132:133], v[132:133], v[194:195]
	v_pk_add_f32 v[134:135], v[134:135], v[196:197]
	v_pk_add_f32 v[116:117], v[116:117], v[208:209]
	v_pk_add_f32 v[118:119], v[118:119], v[210:211]
	v_mul_f32_e32 v220, v132, v132
	v_fmac_f32_e32 v220, v133, v133
	v_fmac_f32_e32 v220, v134, v134
	v_fmac_f32_e32 v220, v135, v135
	v_fmac_f32_e32 v220, v116, v116
	v_fmac_f32_e32 v220, v117, v117
	v_fmac_f32_e32 v220, v118, v118
	v_fmac_f32_e32 v220, v119, v119
	v_cvt_pk_bf16_f32 v120, v132, v133
	v_cvt_pk_bf16_f32 v121, v134, v135
	v_cvt_pk_bf16_f32 v122, v116, v117
	v_cvt_pk_bf16_f32 v123, v118, v119
	global_store_dwordx4 v228, v[120:123], s[4:5] offset:256
	s_waitcnt vmcnt(14)
	v_add_u32_e32 v229, 0x8000, v228
	v_lshlrev_b32_e32 v194, 16, v124
	v_and_b32_e32 v195, 0xffff0000, v124
	v_lshlrev_b32_e32 v196, 16, v125
	v_and_b32_e32 v197, 0xffff0000, v125
	v_lshlrev_b32_e32 v208, 16, v126
	v_and_b32_e32 v209, 0xffff0000, v126
	v_lshlrev_b32_e32 v210, 16, v127
	v_and_b32_e32 v211, 0xffff0000, v127
	v_pk_add_f32 v[108:109], v[108:109], v[194:195]
	v_pk_add_f32 v[110:111], v[110:111], v[196:197]
	v_pk_add_f32 v[104:105], v[104:105], v[208:209]
	v_pk_add_f32 v[106:107], v[106:107], v[210:211]
	v_mul_f32_e32 v213, v108, v108
	v_fmac_f32_e32 v213, v109, v109
	v_fmac_f32_e32 v213, v110, v110
	v_fmac_f32_e32 v213, v111, v111
	v_fmac_f32_e32 v213, v104, v104
	v_fmac_f32_e32 v213, v105, v105
	v_fmac_f32_e32 v213, v106, v106
	v_fmac_f32_e32 v213, v107, v107
	v_cvt_pk_bf16_f32 v124, v108, v109
	v_cvt_pk_bf16_f32 v125, v110, v111
	v_cvt_pk_bf16_f32 v126, v104, v105
	v_cvt_pk_bf16_f32 v127, v106, v107
	global_store_dwordx4 v229, v[124:127], s[4:5]
	v_lshlrev_b32_e32 v194, 16, v128
	v_and_b32_e32 v195, 0xffff0000, v128
	v_lshlrev_b32_e32 v196, 16, v129
	v_and_b32_e32 v197, 0xffff0000, v129
	v_lshlrev_b32_e32 v208, 16, v130
	v_and_b32_e32 v209, 0xffff0000, v130
	v_lshlrev_b32_e32 v210, 16, v131
	v_and_b32_e32 v211, 0xffff0000, v131
	v_pk_add_f32 v[100:101], v[100:101], v[194:195]
	v_pk_add_f32 v[102:103], v[102:103], v[196:197]
	v_pk_add_f32 v[96:97], v[96:97], v[208:209]
	v_pk_add_f32 v[98:99], v[98:99], v[210:211]
	v_mul_f32_e32 v221, v100, v100
	v_fmac_f32_e32 v221, v101, v101
	v_fmac_f32_e32 v221, v102, v102
	v_fmac_f32_e32 v221, v103, v103
	v_fmac_f32_e32 v221, v96, v96
	v_fmac_f32_e32 v221, v97, v97
	v_fmac_f32_e32 v221, v98, v98
	v_fmac_f32_e32 v221, v99, v99
	v_cvt_pk_bf16_f32 v128, v100, v101
	v_cvt_pk_bf16_f32 v129, v102, v103
	v_cvt_pk_bf16_f32 v130, v96, v97
	v_cvt_pk_bf16_f32 v131, v98, v99
	global_store_dwordx4 v229, v[128:131], s[4:5] offset:256
	s_waitcnt vmcnt(14)
; __device__ __forceinline__ unsigned cvt_pk_bf16(float lo, float hi) { unsigned r; asm volatile("v_cvt_pk_bf16_f32 %0, %1, %2" : "=v"(r) : "v"(lo), "v"(hi)); return r; }
;     __device__ __forceinline__ void operator()(const f32x4 (&acc)[2][2][4][2], const Unit& u, int wr, int wc, int fr, int fq) const {
;     ...
;             for (int m = 0; m < 4; ++m) { const int row = row0 + ai * HALF + m * 16; const size_t off = (size_t)row * 1024 + col0; float ss = 0.f;
; #pragma unroll
;                 for (int bj = 0; bj < 2; ++bj) {
;                     const u32x4 b = bw[ai][m][bj];
;                     const f32x4 b0 = (f32x4){__uint_as_float(b.x << 16), __uint_as_float(b.x & 0xffff0000u), __uint_as_float(b.y << 16), __uint_as_float(b.y & 0xffff0000u)};
;                     const f32x4 b1 = (f32x4){__uint_as_float(b.z << 16), __uint_as_float(b.z & 0xffff0000u), __uint_as_float(b.w << 16), __uint_as_float(b.w & 0xffff0000u)};
;                     const f32x4 v0 = acc[ai][bj][m][0] + b0, v1 = acc[ai][bj][m][1] + b1;
;                     ss += (v0[0] * v0[0] + v0[1] * v0[1]) + (v0[2] * v0[2] + v0[3] * v0[3]) + (v1[0] * v1[0] + v1[1] * v1[1]) + (v1[2] * v1[2] + v1[3] * v1[3]);
;                     u32x4 w; w.x = cvt_pk_bf16(v0[0], v0[1]); w.y = cvt_pk_bf16(v0[2], v0[3]); w.z = cvt_pk_bf16(v1[0], v1[1]); w.w = cvt_pk_bf16(v1[2], v1[3]);
;                     *(u32x4*)(hb + off + bj * HALF) = w; }
	v_add_u32_e32 v229, 0x10000, v228
	v_lshlrev_b32_e32 v194, 16, v136
	v_and_b32_e32 v195, 0xffff0000, v136
	v_lshlrev_b32_e32 v196, 16, v137
	v_and_b32_e32 v197, 0xffff0000, v137
	v_lshlrev_b32_e32 v208, 16, v138
	v_and_b32_e32 v209, 0xffff0000, v138
	v_lshlrev_b32_e32 v210, 16, v139
	v_and_b32_e32 v211, 0xffff0000, v139
	v_pk_add_f32 v[92:93], v[92:93], v[194:195]
	v_pk_add_f32 v[94:95], v[94:95], v[196:197]
	v_pk_add_f32 v[88:89], v[88:89], v[208:209]
	v_pk_add_f32 v[90:91], v[90:91], v[210:211]
	v_mul_f32_e32 v214, v92, v92
	v_fmac_f32_e32 v214, v93, v93
	v_fmac_f32_e32 v214, v94, v94
	v_fmac_f32_e32 v214, v95, v95
	v_fmac_f32_e32 v214, v88, v88
	v_fmac_f32_e32 v214, v89, v89
	v_fmac_f32_e32 v214, v90, v90
	v_fmac_f32_e32 v214, v91, v91
	v_cvt_pk_bf16_f32 v136, v92, v93
	v_cvt_pk_bf16_f32 v137, v94, v95
	v_cvt_pk_bf16_f32 v138, v88, v89
	v_cvt_pk_bf16_f32 v139, v90, v91
	global_store_dwordx4 v229, v[136:139], s[4:5]
	v_lshlrev_b32_e32 v194, 16, v140
	v_and_b32_e32 v195, 0xffff0000, v140
	v_lshlrev_b32_e32 v196, 16, v141
	v_and_b32_e32 v197, 0xffff0000, v141
	v_lshlrev_b32_e32 v208, 16, v142
	v_and_b32_e32 v209, 0xffff0000, v142
	v_lshlrev_b32_e32 v210, 16, v143
	v_and_b32_e32 v211, 0xffff0000, v143
	v_pk_add_f32 v[84:85], v[84:85], v[194:195]
	v_pk_add_f32 v[86:87], v[86:87], v[196:197]
	v_pk_add_f32 v[80:81], v[80:81], v[208:209]
	v_pk_add_f32 v[82:83], v[82:83], v[210:211]
	v_mul_f32_e32 v222, v84, v84
	v_fmac_f32_e32 v222, v85, v85
	v_fmac_f32_e32 v222, v86, v86
	v_fmac_f32_e32 v222, v87, v87
	v_fmac_f32_e32 v222, v80, v80
	v_fmac_f32_e32 v222, v81, v81
	v_fmac_f32_e32 v222, v82, v82
	v_fmac_f32_e32 v222, v83, v83
	v_cvt_pk_bf16_f32 v140, v84, v85
	v_cvt_pk_bf16_f32 v141, v86, v87
	v_cvt_pk_bf16_f32 v142, v80, v81
	v_cvt_pk_bf16_f32 v143, v82, v83
	global_store_dwordx4 v229, v[140:143], s[4:5] offset:256
	s_waitcnt vmcnt(14)
	v_add_u32_e32 v229, 0x18000, v228
	v_lshlrev_b32_e32 v194, 16, v144
	v_and_b32_e32 v195, 0xffff0000, v144
	v_lshlrev_b32_e32 v196, 16, v145
	v_and_b32_e32 v197, 0xffff0000, v145
	v_lshlrev_b32_e32 v208, 16, v146
	v_and_b32_e32 v209, 0xffff0000, v146
	v_lshlrev_b32_e32 v210, 16, v147
	v_and_b32_e32 v211, 0xffff0000, v147
	v_pk_add_f32 v[76:77], v[76:77], v[194:195]
	v_pk_add_f32 v[78:79], v[78:79], v[196:197]
	v_pk_add_f32 v[72:73], v[72:73], v[208:209]
	v_pk_add_f32 v[74:75], v[74:75], v[210:211]
	v_mul_f32_e32 v215, v76, v76
	v_fmac_f32_e32 v215, v77, v77
	v_fmac_f32_e32 v215, v78, v78
	v_fmac_f32_e32 v215, v79, v79
	v_fmac_f32_e32 v215, v72, v72
	v_fmac_f32_e32 v215, v73, v73
	v_fmac_f32_e32 v215, v74, v74
	v_fmac_f32_e32 v215, v75, v75
	v_cvt_pk_bf16_f32 v144, v76, v77
	v_cvt_pk_bf16_f32 v145, v78, v79
	v_cvt_pk_bf16_f32 v146, v72, v73
	v_cvt_pk_bf16_f32 v147, v74, v75
	global_store_dwordx4 v229, v[144:147], s[4:5]
	v_lshlrev_b32_e32 v194, 16, v156
	v_and_b32_e32 v195, 0xffff0000, v156
	v_lshlrev_b32_e32 v196, 16, v157
	v_and_b32_e32 v197, 0xffff0000, v157
	v_lshlrev_b32_e32 v208, 16, v158
	v_and_b32_e32 v209, 0xffff0000, v158
	v_lshlrev_b32_e32 v210, 16, v159
	v_and_b32_e32 v211, 0xffff0000, v159
	v_pk_add_f32 v[68:69], v[68:69], v[194:195]
	v_pk_add_f32 v[70:71], v[70:71], v[196:197]
	v_pk_add_f32 v[64:65], v[64:65], v[208:209]
	v_pk_add_f32 v[66:67], v[66:67], v[210:211]
	v_mul_f32_e32 v223, v68, v68
	v_fmac_f32_e32 v223, v69, v69
	v_fmac_f32_e32 v223, v70, v70
	v_fmac_f32_e32 v223, v71, v71
	v_fmac_f32_e32 v223, v64, v64
	v_fmac_f32_e32 v223, v65, v65
	v_fmac_f32_e32 v223, v66, v66
	v_fmac_f32_e32 v223, v67, v67
	v_cvt_pk_bf16_f32 v156, v68, v69
	v_cvt_pk_bf16_f32 v157, v70, v71
	v_cvt_pk_bf16_f32 v158, v64, v65
	v_cvt_pk_bf16_f32 v159, v66, v67
	global_store_dwordx4 v229, v[156:159], s[4:5] offset:256
	s_waitcnt vmcnt(14)
	v_add_u32_e32 v229, 0x40000, v228
	v_lshlrev_b32_e32 v194, 16, v160
	v_and_b32_e32 v195, 0xffff0000, v160
	v_lshlrev_b32_e32 v196, 16, v161
	v_and_b32_e32 v197, 0xffff0000, v161
	v_lshlrev_b32_e32 v208, 16, v162
	v_and_b32_e32 v209, 0xffff0000, v162
	v_lshlrev_b32_e32 v210, 16, v163
	v_and_b32_e32 v211, 0xffff0000, v163
	v_pk_add_f32 v[60:61], v[60:61], v[194:195]
	v_pk_add_f32 v[62:63], v[62:63], v[196:197]
	v_pk_add_f32 v[56:57], v[56:57], v[208:209]
	v_pk_add_f32 v[58:59], v[58:59], v[210:211]
	v_mul_f32_e32 v216, v60, v60
	v_fmac_f32_e32 v216, v61, v61
	v_fmac_f32_e32 v216, v62, v62
	v_fmac_f32_e32 v216, v63, v63
	v_fmac_f32_e32 v216, v56, v56
	v_fmac_f32_e32 v216, v57, v57
	v_fmac_f32_e32 v216, v58, v58
	v_fmac_f32_e32 v216, v59, v59
	v_cvt_pk_bf16_f32 v160, v60, v61
	v_cvt_pk_bf16_f32 v161, v62, v63
	v_cvt_pk_bf16_f32 v162, v56, v57
	v_cvt_pk_bf16_f32 v163, v58, v59
	global_store_dwordx4 v229, v[160:163], s[4:5]
	v_lshlrev_b32_e32 v194, 16, v164
	v_and_b32_e32 v195, 0xffff0000, v164
	v_lshlrev_b32_e32 v196, 16, v165
	v_and_b32_e32 v197, 0xffff0000, v165
	v_lshlrev_b32_e32 v208, 16, v166
	v_and_b32_e32 v209, 0xffff0000, v166
	v_lshlrev_b32_e32 v210, 16, v167
	v_and_b32_e32 v211, 0xffff0000, v167
	v_pk_add_f32 v[52:53], v[52:53], v[194:195]
	v_pk_add_f32 v[54:55], v[54:55], v[196:197]
	v_pk_add_f32 v[48:49], v[48:49], v[208:209]
	v_pk_add_f32 v[50:51], v[50:51], v[210:211]
	v_mul_f32_e32 v224, v52, v52
	v_fmac_f32_e32 v224, v53, v53
	v_fmac_f32_e32 v224, v54, v54
	v_fmac_f32_e32 v224, v55, v55
	v_fmac_f32_e32 v224, v48, v48
	v_fmac_f32_e32 v224, v49, v49
	v_fmac_f32_e32 v224, v50, v50
	v_fmac_f32_e32 v224, v51, v51
	v_cvt_pk_bf16_f32 v164, v52, v53
	v_cvt_pk_bf16_f32 v165, v54, v55
	v_cvt_pk_bf16_f32 v166, v48, v49
	v_cvt_pk_bf16_f32 v167, v50, v51
	global_store_dwordx4 v229, v[164:167], s[4:5] offset:256
	s_waitcnt vmcnt(14)
; __device__ __forceinline__ unsigned cvt_pk_bf16(float lo, float hi) { unsigned r; asm volatile("v_cvt_pk_bf16_f32 %0, %1, %2" : "=v"(r) : "v"(lo), "v"(hi)); return r; }
;     __device__ __forceinline__ void operator()(const f32x4 (&acc)[2][2][4][2], const Unit& u, int wr, int wc, int fr, int fq) const {
;     ...
;             for (int m = 0; m < 4; ++m) { const int row = row0 + ai * HALF + m * 16; const size_t off = (size_t)row * 1024 + col0; float ss = 0.f;
; #pragma unroll
;                 for (int bj = 0; bj < 2; ++bj) {
;                     const u32x4 b = bw[ai][m][bj];
;                     const f32x4 b0 = (f32x4){__uint_as_float(b.x << 16), __uint_as_float(b.x & 0xffff0000u), __uint_as_float(b.y << 16), __uint_as_float(b.y & 0xffff0000u)};
;                     const f32x4 b1 = (f32x4){__uint_as_float(b.z << 16), __uint_as_float(b.z & 0xffff0000u), __uint_as_float(b.w << 16), __uint_as_float(b.w & 0xffff0000u)};
;                     const f32x4 v0 = acc[ai][bj][m][0] + b0, v1 = acc[ai][bj][m][1] + b1;
;                     ss += (v0[0] * v0[0] + v0[1] * v0[1]) + (v0[2] * v0[2] + v0[3] * v0[3]) + (v1[0] * v1[0] + v1[1] * v1[1]) + (v1[2] * v1[2] + v1[3] * v1[3]);
;                     u32x4 w; w.x = cvt_pk_bf16(v0[0], v0[1]); w.y = cvt_pk_bf16(v0[2], v0[3]); w.z = cvt_pk_bf16(v1[0], v1[1]); w.w = cvt_pk_bf16(v1[2], v1[3]);
;                     *(u32x4*)(hb + off + bj * HALF) = w; }
	v_add_u32_e32 v229, 0x48000, v228
	v_lshlrev_b32_e32 v194, 16, v168
	v_and_b32_e32 v195, 0xffff0000, v168
	v_lshlrev_b32_e32 v196, 16, v169
	v_and_b32_e32 v197, 0xffff0000, v169
	v_lshlrev_b32_e32 v208, 16, v170
	v_and_b32_e32 v209, 0xffff0000, v170
	v_lshlrev_b32_e32 v210, 16, v171
	v_and_b32_e32 v211, 0xffff0000, v171
	v_pk_add_f32 v[44:45], v[44:45], v[194:195]
	v_pk_add_f32 v[46:47], v[46:47], v[196:197]
	v_pk_add_f32 v[40:41], v[40:41], v[208:209]
	v_pk_add_f32 v[42:43], v[42:43], v[210:211]
	v_mul_f32_e32 v217, v44, v44
	v_fmac_f32_e32 v217, v45, v45
	v_fmac_f32_e32 v217, v46, v46
	v_fmac_f32_e32 v217, v47, v47
	v_fmac_f32_e32 v217, v40, v40
	v_fmac_f32_e32 v217, v41, v41
	v_fmac_f32_e32 v217, v42, v42
	v_fmac_f32_e32 v217, v43, v43
	v_cvt_pk_bf16_f32 v168, v44, v45
	v_cvt_pk_bf16_f32 v169, v46, v47
	v_cvt_pk_bf16_f32 v170, v40, v41
	v_cvt_pk_bf16_f32 v171, v42, v43
	global_store_dwordx4 v229, v[168:171], s[4:5]
	v_lshlrev_b32_e32 v194, 16, v172
	v_and_b32_e32 v195, 0xffff0000, v172
	v_lshlrev_b32_e32 v196, 16, v173
	v_and_b32_e32 v197, 0xffff0000, v173
	v_lshlrev_b32_e32 v208, 16, v174
	v_and_b32_e32 v209, 0xffff0000, v174
	v_lshlrev_b32_e32 v210, 16, v175
	v_and_b32_e32 v211, 0xffff0000, v175
	v_pk_add_f32 v[36:37], v[36:37], v[194:195]
	v_pk_add_f32 v[38:39], v[38:39], v[196:197]
	v_pk_add_f32 v[32:33], v[32:33], v[208:209]
	v_pk_add_f32 v[34:35], v[34:35], v[210:211]
	v_mul_f32_e32 v225, v36, v36
	v_fmac_f32_e32 v225, v37, v37
	v_fmac_f32_e32 v225, v38, v38
	v_fmac_f32_e32 v225, v39, v39
	v_fmac_f32_e32 v225, v32, v32
	v_fmac_f32_e32 v225, v33, v33
	v_fmac_f32_e32 v225, v34, v34
	v_fmac_f32_e32 v225, v35, v35
	v_cvt_pk_bf16_f32 v172, v36, v37
	v_cvt_pk_bf16_f32 v173, v38, v39
	v_cvt_pk_bf16_f32 v174, v32, v33
	v_cvt_pk_bf16_f32 v175, v34, v35
	global_store_dwordx4 v229, v[172:175], s[4:5] offset:256
	s_waitcnt vmcnt(14)
	v_add_u32_e32 v229, 0x50000, v228
	v_lshlrev_b32_e32 v194, 16, v176
	v_and_b32_e32 v195, 0xffff0000, v176
	v_lshlrev_b32_e32 v196, 16, v177
	v_and_b32_e32 v197, 0xffff0000, v177
	v_lshlrev_b32_e32 v208, 16, v178
	v_and_b32_e32 v209, 0xffff0000, v178
	v_lshlrev_b32_e32 v210, 16, v179
	v_and_b32_e32 v211, 0xffff0000, v179
	v_pk_add_f32 v[28:29], v[28:29], v[194:195]
	v_pk_add_f32 v[30:31], v[30:31], v[196:197]
	v_pk_add_f32 v[24:25], v[24:25], v[208:209]
	v_pk_add_f32 v[26:27], v[26:27], v[210:211]
	v_mul_f32_e32 v218, v28, v28
	v_fmac_f32_e32 v218, v29, v29
	v_fmac_f32_e32 v218, v30, v30
	v_fmac_f32_e32 v218, v31, v31
	v_fmac_f32_e32 v218, v24, v24
	v_fmac_f32_e32 v218, v25, v25
	v_fmac_f32_e32 v218, v26, v26
	v_fmac_f32_e32 v218, v27, v27
	v_cvt_pk_bf16_f32 v176, v28, v29
	v_cvt_pk_bf16_f32 v177, v30, v31
	v_cvt_pk_bf16_f32 v178, v24, v25
	v_cvt_pk_bf16_f32 v179, v26, v27
	global_store_dwordx4 v229, v[176:179], s[4:5]
	v_lshlrev_b32_e32 v194, 16, v180
	v_and_b32_e32 v195, 0xffff0000, v180
	v_lshlrev_b32_e32 v196, 16, v181
	v_and_b32_e32 v197, 0xffff0000, v181
	v_lshlrev_b32_e32 v208, 16, v182
	v_and_b32_e32 v209, 0xffff0000, v182
	v_lshlrev_b32_e32 v210, 16, v183
	v_and_b32_e32 v211, 0xffff0000, v183
	v_pk_add_f32 v[20:21], v[20:21], v[194:195]
	v_pk_add_f32 v[22:23], v[22:23], v[196:197]
	v_pk_add_f32 v[16:17], v[16:17], v[208:209]
	v_pk_add_f32 v[18:19], v[18:19], v[210:211]
	v_mul_f32_e32 v226, v20, v20
	v_fmac_f32_e32 v226, v21, v21
	v_fmac_f32_e32 v226, v22, v22
	v_fmac_f32_e32 v226, v23, v23
	v_fmac_f32_e32 v226, v16, v16
	v_fmac_f32_e32 v226, v17, v17
	v_fmac_f32_e32 v226, v18, v18
	v_fmac_f32_e32 v226, v19, v19
	v_cvt_pk_bf16_f32 v180, v20, v21
	v_cvt_pk_bf16_f32 v181, v22, v23
	v_cvt_pk_bf16_f32 v182, v16, v17
	v_cvt_pk_bf16_f32 v183, v18, v19
	global_store_dwordx4 v229, v[180:183], s[4:5] offset:256
	s_waitcnt vmcnt(14)
; __device__ __forceinline__ unsigned cvt_pk_bf16(float lo, float hi) { unsigned r; asm volatile("v_cvt_pk_bf16_f32 %0, %1, %2" : "=v"(r) : "v"(lo), "v"(hi)); return r; }
;     __device__ __forceinline__ void operator()(const f32x4 (&acc)[2][2][4][2], const Unit& u, int wr, int wc, int fr, int fq) const {
;     ...
;             for (int m = 0; m < 4; ++m) { const int row = row0 + ai * HALF + m * 16; const size_t off = (size_t)row * 1024 + col0; float ss = 0.f;
; #pragma unroll
;                 for (int bj = 0; bj < 2; ++bj) {
;                     const u32x4 b = bw[ai][m][bj];
;                     const f32x4 b0 = (f32x4){__uint_as_float(b.x << 16), __uint_as_float(b.x & 0xffff0000u), __uint_as_float(b.y << 16), __uint_as_float(b.y & 0xffff0000u)};
;                     const f32x4 b1 = (f32x4){__uint_as_float(b.z << 16), __uint_as_float(b.z & 0xffff0000u), __uint_as_float(b.w << 16), __uint_as_float(b.w & 0xffff0000u)};
;                     const f32x4 v0 = acc[ai][bj][m][0] + b0, v1 = acc[ai][bj][m][1] + b1;
;                     ss += (v0[0] * v0[0] + v0[1] * v0[1]) + (v0[2] * v0[2] + v0[3] * v0[3]) + (v1[0] * v1[0] + v1[1] * v1[1]) + (v1[2] * v1[2] + v1[3] * v1[3]);
;                     u32x4 w; w.x = cvt_pk_bf16(v0[0], v0[1]); w.y = cvt_pk_bf16(v0[2], v0[3]); w.z = cvt_pk_bf16(v1[0], v1[1]); w.w = cvt_pk_bf16(v1[2], v1[3]);
;                     *(u32x4*)(hb + off + bj * HALF) = w; }
;                 ss += __shfl_xor(ss, 16); ss += __shfl_xor(ss, 32);
;                 if (fq == 0) slots[(size_t)row * 16 + u.pn * 4 + wc] = ss; }
	v_add_u32_e32 v229, 0x58000, v228
	v_lshlrev_b32_e32 v194, 16, v184
	v_and_b32_e32 v195, 0xffff0000, v184
	v_lshlrev_b32_e32 v196, 16, v185
	v_and_b32_e32 v197, 0xffff0000, v185
	v_lshlrev_b32_e32 v208, 16, v186
	v_and_b32_e32 v209, 0xffff0000, v186
	v_lshlrev_b32_e32 v210, 16, v187
	v_and_b32_e32 v211, 0xffff0000, v187
	v_pk_add_f32 v[12:13], v[12:13], v[194:195]
	v_pk_add_f32 v[14:15], v[14:15], v[196:197]
	v_pk_add_f32 v[8:9], v[8:9], v[208:209]
	v_pk_add_f32 v[10:11], v[10:11], v[210:211]
	v_mul_f32_e32 v219, v12, v12
	v_fmac_f32_e32 v219, v13, v13
	v_fmac_f32_e32 v219, v14, v14
	v_fmac_f32_e32 v219, v15, v15
	v_fmac_f32_e32 v219, v8, v8
	v_fmac_f32_e32 v219, v9, v9
	v_fmac_f32_e32 v219, v10, v10
	v_fmac_f32_e32 v219, v11, v11
	v_cvt_pk_bf16_f32 v184, v12, v13
	v_cvt_pk_bf16_f32 v185, v14, v15
	v_cvt_pk_bf16_f32 v186, v8, v9
	v_cvt_pk_bf16_f32 v187, v10, v11
	global_store_dwordx4 v229, v[184:187], s[4:5]
	v_lshlrev_b32_e32 v194, 16, v188
	v_and_b32_e32 v195, 0xffff0000, v188
	v_lshlrev_b32_e32 v196, 16, v189
	v_and_b32_e32 v197, 0xffff0000, v189
	v_lshlrev_b32_e32 v208, 16, v190
	v_and_b32_e32 v209, 0xffff0000, v190
	v_lshlrev_b32_e32 v210, 16, v191
	v_and_b32_e32 v211, 0xffff0000, v191
	v_pk_add_f32 v[4:5], v[4:5], v[194:195]
	v_pk_add_f32 v[6:7], v[6:7], v[196:197]
	v_pk_add_f32 v[0:1], v[0:1], v[208:209]
	v_pk_add_f32 v[2:3], v[2:3], v[210:211]
	v_mul_f32_e32 v227, v4, v4
	v_fmac_f32_e32 v227, v5, v5
	v_fmac_f32_e32 v227, v6, v6
	v_fmac_f32_e32 v227, v7, v7
	v_fmac_f32_e32 v227, v0, v0
	v_fmac_f32_e32 v227, v1, v1
	v_fmac_f32_e32 v227, v2, v2
	v_fmac_f32_e32 v227, v3, v3
	v_cvt_pk_bf16_f32 v188, v4, v5
	v_cvt_pk_bf16_f32 v189, v6, v7
	v_cvt_pk_bf16_f32 v190, v0, v1
	v_cvt_pk_bf16_f32 v191, v2, v3
	global_store_dwordx4 v229, v[188:191], s[4:5] offset:256
	v_add_f32_e32 v212, v212, v220
	v_add_f32_e32 v213, v213, v221
	v_add_f32_e32 v214, v214, v222
	v_add_f32_e32 v215, v215, v223
	v_add_f32_e32 v216, v216, v224
	v_add_f32_e32 v217, v217, v225
	v_add_f32_e32 v218, v218, v226
	v_add_f32_e32 v219, v219, v227
	ds_bpermute_b32 v232, v230, v212
	ds_bpermute_b32 v233, v230, v213
	ds_bpermute_b32 v234, v230, v214
	ds_bpermute_b32 v235, v230, v215
	ds_bpermute_b32 v236, v230, v216
	ds_bpermute_b32 v237, v230, v217
	ds_bpermute_b32 v238, v230, v218
	ds_bpermute_b32 v239, v230, v219
	s_waitcnt lgkmcnt(0)
	v_add_f32_e32 v212, v212, v232
	v_add_f32_e32 v213, v213, v233
	v_add_f32_e32 v214, v214, v234
	v_add_f32_e32 v215, v215, v235
	v_add_f32_e32 v216, v216, v236
	v_add_f32_e32 v217, v217, v237
	v_add_f32_e32 v218, v218, v238
	v_add_f32_e32 v219, v219, v239
	ds_bpermute_b32 v232, v231, v212
	ds_bpermute_b32 v233, v231, v213
	ds_bpermute_b32 v234, v231, v214
	ds_bpermute_b32 v235, v231, v215
	ds_bpermute_b32 v236, v231, v216
	ds_bpermute_b32 v237, v231, v217
	ds_bpermute_b32 v238, v231, v218
	ds_bpermute_b32 v239, v231, v219
	s_waitcnt lgkmcnt(0)
	v_add_f32_e32 v212, v212, v232
	v_add_f32_e32 v213, v213, v233
	v_add_f32_e32 v214, v214, v234
	v_add_f32_e32 v215, v215, v235
	v_add_f32_e32 v216, v216, v236
	v_add_f32_e32 v217, v217, v237
	v_add_f32_e32 v218, v218, v238
	v_add_f32_e32 v219, v219, v239
	s_and_saveexec_b64 s[20:21], s[38:39]
	global_store_dword v240, v212, s[8:9]
	global_store_dword v240, v213, s[8:9] offset:1024
	global_store_dword v240, v214, s[8:9] offset:2048
	global_store_dword v240, v215, s[8:9] offset:3072
	global_store_dword v241, v216, s[8:9]
	global_store_dword v241, v217, s[8:9] offset:1024
	global_store_dword v241, v218, s[8:9] offset:2048
	global_store_dword v241, v219, s[8:9] offset:3072
	s_or_b64 exec, exec, s[20:21]
	s_movk_i32 s29, 0x1600
	s_and_b64 vcc, exec, s[40:41]
	s_mov_b64 s[16:17], -1
	s_cbranch_vccnz .LBB0_1019
	s_andn2_b64 vcc, exec, s[0:1]
	s_cbranch_vccnz .LBB0_1018
	s_barrier
	s_branch .LBB0_1018
